# comb10 + one-deep row prefetch in the norm2(l0) / norm1(l1) RMS-norm row loops
# speedup vs baseline: 1.0166x; 1.0166x over previous
; template <int PH> __device__ __forceinline__ void phase_body(const Args& args, LAS unsigned char* lds) {
;     ...
;                     for (int R = 4 * gw; R < MR; R += 4 * NGW) { const int b = R / NT, n = R - b * NT; const bool isc = n >= TL;
;                         if (isc && sub == 5 && l == 1) continue;
;                         const bf16_t* xr = XR + (size_t)R * DM + lane * 4; const float* mp = modl + (isc ? 32 : b) * 6144 + lane * 4;
;                         u32x2 q[4][4]; float ss[4];
; #pragma unroll
;                         for (int rw = 0; rw < 4; ++rw)
; #pragma unroll
;                             for (int j = 0; j < 4; ++j) q[rw][j] = *(const u32x2*)(xr + (size_t)rw * DM + 256 * j);
.LBB0_978:
	s_cmp_gt_i32 s76, 6
	s_cselect_b64 s[2:3], -1, 0
	s_cmp_lt_i32 s77, 7
	s_cselect_b64 s[4:5], -1, 0
	s_or_b64 s[2:3], s[2:3], s[4:5]
	s_and_b64 vcc, exec, s[2:3]
	s_cbranch_vccnz .LBB0_1046
	v_and_b32_e32 v1, 0x3ff, v0
	v_mov_b32_e32 v2, v1
	s_add_u32 s8, s0, 0xb8
	s_load_dword s21, s[0:1], 0xb8
	s_addc_u32 s9, s1, 0
	v_readfirstlane_b32 s2, v2
	s_ashr_i32 s2, s2, 4
	s_lshl_b32 s3, s26, 5
	s_and_b32 s2, s2, -4
	s_add_i32 s10, s2, s3
	s_cmp_gt_i32 s10, 0x11fff
	s_cbranch_scc1 .LBB0_982
	s_waitcnt lgkmcnt(0)
	v_lshlrev_b32_e32 v3, 4, v2
	v_and_b32_e32 v10, 0x3f0, v3
	v_mov_b32_e32 v11, 0
	v_mbcnt_lo_u32_b32 v3, -1, 0
	v_lshl_add_u64 v[4:5], s[30:31], 0, v[10:11]
	s_mov_b64 s[2:3], 0x44e0000
	v_mbcnt_hi_u32_b32 v3, -1, v3
	v_lshl_add_u64 v[12:13], v[4:5], 0, s[2:3]
	v_and_b32_e32 v4, 64, v3
	v_add_u32_e32 v4, 64, v4
	v_xor_b32_e32 v5, 1, v3
	v_cmp_lt_i32_e32 vcc, v5, v4
	s_ashr_i32 s11, s10, 31
	s_lshl_b32 s12, s21, 5
	v_cndmask_b32_e32 v5, v3, v5, vcc
	v_lshlrev_b32_e32 v82, 2, v5
	v_xor_b32_e32 v5, 2, v3
	v_cmp_lt_i32_e32 vcc, v5, v4
	s_lshl_b64 s[2:3], s[10:11], 11
	s_add_u32 s14, s30, s2
	v_cndmask_b32_e32 v5, v3, v5, vcc
	v_lshlrev_b32_e32 v83, 2, v5
	v_xor_b32_e32 v5, 4, v3
	v_cmp_lt_i32_e32 vcc, v5, v4
	s_addc_u32 s15, s31, s3
	s_ashr_i32 s13, s12, 31
	v_cndmask_b32_e32 v5, v3, v5, vcc
	v_lshlrev_b32_e32 v84, 2, v5
	v_xor_b32_e32 v5, 8, v3
	v_cmp_lt_i32_e32 vcc, v5, v4
	s_lshl_b64 s[16:17], s[12:13], 11
	v_and_b32_e32 v2, 63, v2
	v_cndmask_b32_e32 v5, v3, v5, vcc
	v_lshlrev_b32_e32 v85, 2, v5
	v_xor_b32_e32 v5, 16, v3
	v_cmp_lt_i32_e32 vcc, v5, v4
	s_add_u32 s18, s28, s2
	s_mov_b32 s2, 0x358637bd
	v_cndmask_b32_e32 v5, v3, v5, vcc
	v_lshlrev_b32_e32 v86, 2, v5
	v_xor_b32_e32 v5, 32, v3
	v_cmp_lt_i32_e32 vcc, v5, v4
	v_lshl_add_u64 v[14:15], s[50:51], 0, v[10:11]
	v_lshlrev_b32_e32 v10, 3, v2
	v_cndmask_b32_e32 v3, v3, v5, vcc
	v_lshlrev_b32_e32 v87, 2, v3
	s_addc_u32 s19, s29, s3
	s_movk_i32 s11, 0x1000
	s_mov_b32 s20, 0x3a800000
	v_mov_b64_e32 v[16:17], s[2:3]
	s_mov_b32 s13, 0x800000
	s_movk_i32 s22, 0x4000
	s_movk_i32 s23, 0x3000
	s_mov_b32 s24, 0x1d92c000
	s_mov_b32 s25, 0x1d92d000
	s_mov_b32 s98, 0x1000
	s_mov_b32 s99, 0
	v_lshl_add_u64 v[232:233], s[18:19], 0, v[10:11]
	v_lshl_add_u64 v[234:235], v[232:233], 0, s[98:99]
	global_load_dwordx2 v[22:23], v[232:233], off
	global_load_dwordx2 v[24:25], v[232:233], off offset:512
	global_load_dwordx2 v[26:27], v[232:233], off offset:1024
	global_load_dwordx2 v[28:29], v[232:233], off offset:1536
	global_load_dwordx2 v[30:31], v[232:233], off offset:2048
	global_load_dwordx2 v[32:33], v[232:233], off offset:2560
	global_load_dwordx2 v[34:35], v[232:233], off offset:3072
	global_load_dwordx2 v[36:37], v[232:233], off offset:3584
	global_load_dwordx2 v[38:39], v[234:235], off
	global_load_dwordx2 v[40:41], v[234:235], off offset:512
	global_load_dwordx2 v[42:43], v[234:235], off offset:1024
	global_load_dwordx2 v[44:45], v[234:235], off offset:1536
	global_load_dwordx2 v[62:63], v[234:235], off offset:2048
	global_load_dwordx2 v[64:65], v[234:235], off offset:2560
	global_load_dwordx2 v[92:93], v[234:235], off offset:3072
	global_load_dwordx2 v[94:95], v[234:235], off offset:3584
.LBB0_981:
	v_lshl_add_u64 v[2:3], s[18:19], 0, v[10:11]
	s_mul_hi_i32 s2, s10, 0x38e38e39
	global_load_dwordx4 v[6:9], v[14:15], off
	v_add_co_u32_e32 v2, vcc, s11, v2
	s_lshr_b32 s3, s2, 31
	s_ashr_i32 s2, s2, 9
	v_addc_co_u32_e32 v3, vcc, 0, v3, vcc
	s_add_i32 s2, s2, s3
	s_mul_i32 s3, s2, 0xfffff700
	v_lshl_add_u64 v[4:5], s[14:15], 0, v[10:11]
	s_add_i32 s3, s10, s3
	v_add_co_u32_e32 v20, vcc, s24, v4
	s_mulk_i32 s2, 0x1800
	s_cmpk_lt_i32 s3, 0x800
	v_addc_co_u32_e32 v21, vcc, 0, v5, vcc
	s_cselect_b32 s2, s2, 0x30000
	v_add_co_u32_e32 v18, vcc, s25, v4
	s_ashr_i32 s3, s2, 31
	s_nop 0
	v_addc_co_u32_e32 v19, vcc, 0, v5, vcc
	v_lshl_add_u64 v[2:3], s[2:3], 2, v[12:13]
	v_add_co_u32_e32 v46, vcc, s22, v2
	s_add_i32 s10, s10, s12
	s_nop 0
	v_addc_co_u32_e32 v47, vcc, 0, v3, vcc
	v_add_co_u32_e32 v48, vcc, s23, v2
	s_add_u32 s14, s14, s16
	s_nop 0
	v_addc_co_u32_e32 v49, vcc, 0, v3, vcc
	global_load_dwordx4 v[88:91], v[46:47], off
	global_load_dwordx4 v[2:5], v[48:49], off
	s_addc_u32 s15, s15, s17
	s_add_u32 s18, s18, s16
	s_addc_u32 s19, s19, s17
	s_cmp_lt_i32 s10, 0x12000
	s_waitcnt vmcnt(0)
	v_mov_b64_e32 v[200:201], v[22:23]
	v_mov_b64_e32 v[202:203], v[24:25]
	v_mov_b64_e32 v[204:205], v[26:27]
	v_mov_b64_e32 v[206:207], v[28:29]
	v_mov_b64_e32 v[208:209], v[30:31]
	v_mov_b64_e32 v[210:211], v[32:33]
	v_mov_b64_e32 v[212:213], v[34:35]
	v_mov_b64_e32 v[214:215], v[36:37]
	v_mov_b64_e32 v[216:217], v[38:39]
	v_mov_b64_e32 v[218:219], v[40:41]
	v_mov_b64_e32 v[220:221], v[42:43]
	v_mov_b64_e32 v[222:223], v[44:45]
	v_mov_b64_e32 v[224:225], v[62:63]
	v_mov_b64_e32 v[226:227], v[64:65]
	v_mov_b64_e32 v[228:229], v[92:93]
	v_mov_b64_e32 v[230:231], v[94:95]
	s_cbranch_scc0 .Lnpf_n0
	v_lshl_add_u64 v[232:233], s[18:19], 0, v[10:11]
	v_lshl_add_u64 v[234:235], v[232:233], 0, s[98:99]
	global_load_dwordx2 v[22:23], v[232:233], off
	global_load_dwordx2 v[24:25], v[232:233], off offset:512
	global_load_dwordx2 v[26:27], v[232:233], off offset:1024
	global_load_dwordx2 v[28:29], v[232:233], off offset:1536
	global_load_dwordx2 v[30:31], v[232:233], off offset:2048
	global_load_dwordx2 v[32:33], v[232:233], off offset:2560
	global_load_dwordx2 v[34:35], v[232:233], off offset:3072
	global_load_dwordx2 v[36:37], v[232:233], off offset:3584
	global_load_dwordx2 v[38:39], v[234:235], off
	global_load_dwordx2 v[40:41], v[234:235], off offset:512
	global_load_dwordx2 v[42:43], v[234:235], off offset:1024
	global_load_dwordx2 v[44:45], v[234:235], off offset:1536
	global_load_dwordx2 v[62:63], v[234:235], off offset:2048
	global_load_dwordx2 v[64:65], v[234:235], off offset:2560
	global_load_dwordx2 v[92:93], v[234:235], off offset:3072
	global_load_dwordx2 v[94:95], v[234:235], off offset:3584
; template <int PH> __device__ __forceinline__ void phase_body(const Args& args, LAS unsigned char* lds) {
;     ...
;                         for (int rw = 0; rw < 4; ++rw) { float s_ = 0.f;
; #pragma unroll
;                             for (int j = 0; j < 4; ++j) { const float a0 = bflo(q[rw][j].x), a1 = bfhi(q[rw][j].x), a2 = bflo(q[rw][j].y), a3 = bfhi(q[rw][j].y); s_ += (a0 * a0 + a1 * a1) + (a2 * a2 + a3 * a3); }
.Lnpf_n0:
	v_and_b32_e32 v97, 0xffff0000, v200
	v_and_b32_e32 v99, 0xffff0000, v201
	v_and_b32_e32 v67, 0xffff0000, v203
	v_and_b32_e32 v66, 0xffff0000, v202
	v_and_b32_e32 v51, 0xffff0000, v204
	v_lshlrev_b32_e32 v54, 16, v205
	v_and_b32_e32 v55, 0xffff0000, v205
	v_lshlrev_b32_e32 v205, 16, v206
	v_and_b32_e32 v101, 0xffff0000, v208
	v_and_b32_e32 v103, 0xffff0000, v209
	v_lshlrev_b32_e32 v96, 16, v200
	v_lshlrev_b32_e32 v98, 16, v201
	v_lshlrev_b32_e32 v75, 16, v203
	v_lshlrev_b32_e32 v74, 16, v202
	v_lshlrev_b32_e32 v50, 16, v204
	v_and_b32_e32 v203, 0xffff0000, v206
	v_lshlrev_b32_e32 v200, 16, v207
	v_and_b32_e32 v201, 0xffff0000, v207
	v_lshlrev_b32_e32 v100, 16, v208
	v_lshlrev_b32_e32 v102, 16, v209
	v_lshlrev_b32_e32 v73, 16, v211
	v_and_b32_e32 v69, 0xffff0000, v211
	v_and_b32_e32 v68, 0xffff0000, v210
	v_and_b32_e32 v53, 0xffff0000, v212
	v_and_b32_e32 v57, 0xffff0000, v213
	v_lshlrev_b32_e32 v211, 16, v214
	v_and_b32_e32 v209, 0xffff0000, v214
	v_lshlrev_b32_e32 v206, 16, v215
	v_and_b32_e32 v207, 0xffff0000, v215
	v_mul_f32_e32 v202, v99, v99
	v_pk_mul_f32 v[104:105], v[66:67], v[66:67]
	v_mul_f32_e32 v204, v97, v97
	v_mov_b32_e32 v107, v205
	v_mul_f32_e32 v208, v51, v51
	v_mul_f32_e32 v214, v103, v103
	v_mul_f32_e32 v106, v101, v101
	v_and_b32_e32 v115, 0xffff0000, v216
	v_and_b32_e32 v117, 0xffff0000, v217
	v_and_b32_e32 v71, 0xffff0000, v219
	v_and_b32_e32 v70, 0xffff0000, v218
	v_and_b32_e32 v215, 0xffff0000, v222
	v_and_b32_e32 v119, 0xffff0000, v224
	v_and_b32_e32 v121, 0xffff0000, v225
	v_lshlrev_b32_e32 v72, 16, v210
	v_lshlrev_b32_e32 v52, 16, v212
	v_lshlrev_b32_e32 v56, 16, v213
	v_mul_f32_e32 v210, v55, v55
	v_pk_mul_f32 v[108:109], v[68:69], v[68:69]
	v_mov_b32_e32 v111, v211
	v_mul_f32_e32 v110, v53, v53
	v_mul_f32_e32 v112, v57, v57
	v_lshlrev_b32_e32 v114, 16, v216
	v_lshlrev_b32_e32 v116, 16, v217
	v_lshlrev_b32_e32 v81, 16, v219
	v_lshlrev_b32_e32 v80, 16, v218
	v_lshlrev_b32_e32 v58, 16, v220
	v_and_b32_e32 v59, 0xffff0000, v220
	v_lshlrev_b32_e32 v60, 16, v221
	v_and_b32_e32 v61, 0xffff0000, v221
	v_lshlrev_b32_e32 v217, 16, v222
	v_lshlrev_b32_e32 v212, 16, v223
	v_and_b32_e32 v213, 0xffff0000, v223
	v_lshlrev_b32_e32 v118, 16, v224
	v_lshlrev_b32_e32 v120, 16, v225
	v_lshlrev_b32_e32 v79, 16, v227
	v_lshlrev_b32_e32 v78, 16, v226
	v_and_b32_e32 v77, 0xffff0000, v227
	v_and_b32_e32 v76, 0xffff0000, v226
	v_lshlrev_b32_e32 v224, 16, v228
	v_and_b32_e32 v225, 0xffff0000, v228
	v_lshlrev_b32_e32 v226, 16, v229
	v_and_b32_e32 v227, 0xffff0000, v229
	v_lshlrev_b32_e32 v223, 16, v230
	v_and_b32_e32 v221, 0xffff0000, v230
	v_lshlrev_b32_e32 v218, 16, v231
	v_and_b32_e32 v219, 0xffff0000, v231
	v_pk_fma_f32 v[228:229], v[98:99], v[98:99], v[202:203] op_sel_hi:[1,1,0]
	v_pk_fma_f32 v[230:231], v[74:75], v[74:75], v[104:105]
	v_pk_fma_f32 v[104:105], v[96:97], v[96:97], v[204:205] op_sel_hi:[1,1,0]
	v_pk_fma_f32 v[122:123], v[50:51], v[50:51], v[208:209] op_sel_hi:[1,1,0]
	v_pk_fma_f32 v[126:127], v[102:103], v[102:103], v[214:215] op_sel_hi:[1,1,0]
	v_pk_fma_f32 v[128:129], v[100:101], v[100:101], v[106:107] op_sel_hi:[1,1,0]
	v_mul_f32_e32 v202, v117, v117
	v_pk_mul_f32 v[132:133], v[70:71], v[70:71]
	v_mul_f32_e32 v208, v115, v115
	v_mul_f32_e32 v220, v121, v121
	v_mul_f32_e32 v222, v119, v119
	v_mul_f32_e32 v140, v200, v200
	v_mul_f32_e32 v141, v201, v201
	v_mul_f32_e32 v142, v206, v206
	v_mul_f32_e32 v143, v207, v207
	v_pk_fma_f32 v[124:125], v[54:55], v[54:55], v[210:211] op_sel_hi:[1,1,0]
	v_pk_fma_f32 v[108:109], v[72:73], v[72:73], v[108:109]
	v_pk_fma_f32 v[130:131], v[52:53], v[52:53], v[110:111] op_sel_hi:[1,1,0]
	v_pk_fma_f32 v[112:113], v[56:57], v[56:57], v[112:113] op_sel_hi:[1,1,0]
	v_mov_b32_e32 v135, v217
	v_mul_f32_e32 v216, v61, v61
	v_pk_mul_f32 v[136:137], v[76:77], v[76:77]
	v_mov_b32_e32 v139, v223
	v_mul_f32_e32 v134, v225, v225
	v_mul_f32_e32 v138, v227, v227
	v_mov_b32_e32 v204, v104
	v_mov_b32_e32 v106, v228
	v_pk_add_f32 v[228:229], v[104:105], v[228:229]
	v_mov_b32_e32 v210, v128
	v_mov_b32_e32 v110, v126
	v_pk_add_f32 v[104:105], v[128:129], v[126:127]
	v_pk_fma_f32 v[126:127], v[116:117], v[116:117], v[202:203] op_sel_hi:[1,1,0]
	v_pk_fma_f32 v[128:129], v[80:81], v[80:81], v[132:133]
	v_pk_fma_f32 v[132:133], v[114:115], v[114:115], v[208:209] op_sel_hi:[1,1,0]
	v_pk_fma_f32 v[144:145], v[120:121], v[120:121], v[220:221] op_sel_hi:[1,1,0]
	v_pk_fma_f32 v[146:147], v[118:119], v[118:119], v[222:223] op_sel_hi:[1,1,0]
	v_mul_f32_e32 v152, v203, v203
	v_mul_f32_e32 v153, v209, v209
	v_mul_f32_e32 v214, v59, v59
	v_pk_add_f32 v[230:231], v[230:231], v[230:231] op_sel:[0,1] op_sel_hi:[1,0]
	v_mov_b32_e32 v123, v140
	v_mov_b32_e32 v125, v141
	v_pk_add_f32 v[108:109], v[108:109], v[108:109] op_sel:[0,1] op_sel_hi:[1,0]
	v_mov_b32_e32 v131, v142
	v_mov_b32_e32 v113, v143
	v_pk_fma_f32 v[142:143], v[60:61], v[60:61], v[216:217] op_sel_hi:[1,1,0]
	v_pk_fma_f32 v[136:137], v[78:79], v[78:79], v[136:137]
	v_pk_fma_f32 v[148:149], v[224:225], v[224:225], v[134:135] op_sel_hi:[1,1,0]
	v_pk_fma_f32 v[150:151], v[226:227], v[226:227], v[138:139] op_sel_hi:[1,1,0]
	v_pk_mul_f32 v[106:107], v[204:205], v[106:107]
	v_pk_mul_f32 v[110:111], v[210:211], v[110:111]
	v_mov_b32_e32 v216, v132
	v_mov_b32_e32 v134, v126
	v_mov_b32_e32 v222, v146
	v_mov_b32_e32 v138, v144
	v_mul_f32_e32 v154, v215, v215
	v_mul_f32_e32 v155, v212, v212
	v_mul_f32_e32 v156, v213, v213
	v_mul_f32_e32 v157, v221, v221
	v_mul_f32_e32 v158, v218, v218
	v_mul_f32_e32 v159, v219, v219
	v_pk_fma_f32 v[140:141], v[58:59], v[58:59], v[214:215] op_sel_hi:[1,1,0]
	v_mov_b32_e32 v231, v152
	v_pk_add_f32 v[122:123], v[122:123], v[124:125]
; __device__ __forceinline__ unsigned cvt_pk(float lo, float hi) { unsigned r; asm volatile("v_cvt_pk_bf16_f32 %0, %1, %2" : "=v"(r) : "v"(lo), "v"(hi)); return r; }
; __device__ __forceinline__ float wave_sum(float v) {
; #pragma unroll
;     for (int o = 1; o < 64; o <<= 1) v += __shfl_xor(v, o);
;     return v;
; template <int PH> __device__ __forceinline__ void phase_body(const Args& args, LAS unsigned char* lds) {
;     ...
;                         for (int rw = 0; rw < 4; ++rw) { float s_ = 0.f;
; #pragma unroll
;                             for (int j = 0; j < 4; ++j) { const float a0 = bflo(q[rw][j].x), a1 = bfhi(q[rw][j].x), a2 = bflo(q[rw][j].y), a3 = bfhi(q[rw][j].y); s_ += (a0 * a0 + a1 * a1) + (a2 * a2 + a3 * a3); }
;                             ss[rw] = rsqrtf(wave_sum(s_) * (1.f / DM) + EPS); }
; #pragma unroll
;                         for (int j = 0; j < 4; ++j) { const f32x4 g4 = *(const f32x4*)(gain + lane * 4 + 256 * j), sc = *(const f32x4*)(mp + scoff + 256 * j) + 1.f, sh = *(const f32x4*)(mp + shoff + 256 * j); const f32x4 gs = g4 * sc;
; #pragma unroll
;                             for (int rw = 0; rw < 4; ++rw) { const f32x4 v = (f32x4){bflo(q[rw][j].x), bfhi(q[rw][j].x), bflo(q[rw][j].y), bfhi(q[rw][j].y)}; const f32x4 y = (v * ss[rw]) * gs + sh; u32x2 w;
;                                 w.x = cvt_pk(y[0], y[1]); w.y = cvt_pk(y[2], y[3]); *(u32x2*)(XC + (size_t)(R + rw) * DM + lane * 4 + 256 * j) = w; } } }
	v_mov_b32_e32 v109, v153
	v_pk_add_f32 v[112:113], v[130:131], v[112:113]
	v_pk_add_f32 v[124:125], v[132:133], v[126:127]
	v_pk_add_f32 v[126:127], v[128:129], v[128:129] op_sel:[0,1] op_sel_hi:[1,0]
	v_pk_add_f32 v[128:129], v[146:147], v[144:145]
	v_pk_add_f32 v[130:131], v[136:137], v[136:137] op_sel:[0,1] op_sel_hi:[1,0]
	v_mov_b32_e32 v229, v107
	v_mov_b32_e32 v105, v111
	v_pk_mul_f32 v[106:107], v[216:217], v[134:135]
	v_pk_mul_f32 v[132:133], v[222:223], v[138:139]
	v_mov_b32_e32 v141, v155
	v_mov_b32_e32 v143, v156
	v_mov_b32_e32 v149, v158
	v_mov_b32_e32 v151, v159
	v_mov_b32_e32 v127, v154
	v_mov_b32_e32 v131, v157
	v_pk_add_f32 v[228:229], v[228:229], v[230:231]
	v_pk_add_f32 v[230:231], v[104:105], v[108:109]
	v_mov_b32_e32 v125, v107
	v_mov_b32_e32 v129, v133
	v_pk_add_f32 v[110:111], v[140:141], v[142:143]
	v_pk_add_f32 v[134:135], v[148:149], v[150:151]
	v_pk_add_f32 v[228:229], v[228:229], v[122:123]
	v_pk_add_f32 v[230:231], v[230:231], v[112:113]
	v_pk_add_f32 v[104:105], v[124:125], v[126:127]
	v_pk_add_f32 v[106:107], v[128:129], v[130:131]
	v_mov_b32_e32 v108, v230
	v_mov_b32_e32 v109, v228
	v_mov_b32_e32 v228, v231
	v_pk_add_f32 v[230:231], v[104:105], v[110:111]
	v_pk_add_f32 v[104:105], v[106:107], v[134:135]
	v_pk_add_f32 v[228:229], v[108:109], v[228:229]
	v_mov_b32_e32 v106, v104
	v_mov_b32_e32 v107, v230
	v_mov_b32_e32 v230, v105
	v_pk_add_f32 v[88:89], v[88:89], 1.0 op_sel_hi:[1,0]
	ds_bpermute_b32 v105, v82, v229
	ds_bpermute_b32 v104, v82, v228
	v_pk_add_f32 v[230:231], v[106:107], v[230:231]
	v_pk_mul_f32 v[88:89], v[6:7], v[88:89]
	ds_bpermute_b32 v7, v82, v231
	ds_bpermute_b32 v6, v82, v230
	v_pk_add_f32 v[90:91], v[90:91], 1.0 op_sel_hi:[1,0]
	v_mov_b32_e32 v214, v217
	v_pk_mul_f32 v[90:91], v[8:9], v[90:91]
	s_waitcnt lgkmcnt(2)
	v_pk_add_f32 v[8:9], v[228:229], v[104:105]
	ds_bpermute_b32 v229, v83, v9
	ds_bpermute_b32 v228, v83, v8
	s_waitcnt lgkmcnt(2)
	v_pk_add_f32 v[6:7], v[230:231], v[6:7]
	ds_bpermute_b32 v231, v83, v7
	ds_bpermute_b32 v230, v83, v6
	v_mov_b32_e32 v220, v223
	s_waitcnt lgkmcnt(2)
	v_pk_add_f32 v[8:9], v[8:9], v[228:229]
	ds_bpermute_b32 v229, v84, v9
	ds_bpermute_b32 v228, v84, v8
	s_waitcnt lgkmcnt(2)
	v_pk_add_f32 v[6:7], v[6:7], v[230:231]
	ds_bpermute_b32 v231, v84, v7
	ds_bpermute_b32 v230, v84, v6
	s_waitcnt lgkmcnt(2)
	v_pk_add_f32 v[8:9], v[8:9], v[228:229]
	ds_bpermute_b32 v229, v85, v9
	ds_bpermute_b32 v228, v85, v8
	s_waitcnt lgkmcnt(2)
	v_pk_add_f32 v[6:7], v[6:7], v[230:231]
	ds_bpermute_b32 v231, v85, v7
	ds_bpermute_b32 v230, v85, v6
	s_waitcnt lgkmcnt(2)
	v_pk_add_f32 v[8:9], v[8:9], v[228:229]
	ds_bpermute_b32 v229, v86, v9
	ds_bpermute_b32 v228, v86, v8
	s_waitcnt lgkmcnt(2)
	v_pk_add_f32 v[6:7], v[6:7], v[230:231]
	ds_bpermute_b32 v231, v86, v7
	ds_bpermute_b32 v230, v86, v6
	s_waitcnt lgkmcnt(2)
	v_pk_add_f32 v[8:9], v[8:9], v[228:229]
	ds_bpermute_b32 v229, v87, v9
	ds_bpermute_b32 v228, v87, v8
	s_waitcnt lgkmcnt(2)
	v_pk_add_f32 v[6:7], v[6:7], v[230:231]
	ds_bpermute_b32 v231, v87, v7
	ds_bpermute_b32 v230, v87, v6
	s_waitcnt lgkmcnt(2)
	v_pk_add_f32 v[8:9], v[8:9], v[228:229]
	s_nop 0
	v_pk_fma_f32 v[8:9], v[8:9], s[20:21], v[16:17] op_sel_hi:[1,0,0]
	s_waitcnt lgkmcnt(0)
	v_pk_add_f32 v[6:7], v[6:7], v[230:231]
	v_mul_f32_e32 v202, 0x4b800000, v9
	v_mul_f32_e32 v204, 0x4b800000, v8
	v_cmp_gt_f32_e32 vcc, s13, v8
	v_pk_fma_f32 v[6:7], v[6:7], s[20:21], v[16:17] op_sel_hi:[1,0,0]
	v_cmp_gt_f32_e64 s[2:3], s13, v9
	v_cndmask_b32_e32 v8, v8, v204, vcc
	v_mul_f32_e32 v204, 0x4b800000, v6
	v_cndmask_b32_e64 v9, v9, v202, s[2:3]
	v_mul_f32_e32 v202, 0x4b800000, v7
	v_cmp_gt_f32_e64 s[4:5], s13, v6
	v_cmp_gt_f32_e64 s[6:7], s13, v7
	v_rsq_f32_e32 v9, v9
	v_rsq_f32_e32 v8, v8
	v_cndmask_b32_e64 v7, v7, v202, s[6:7]
	v_cndmask_b32_e64 v6, v6, v204, s[4:5]
	v_rsq_f32_e32 v7, v7
	v_rsq_f32_e32 v202, v6
	v_mul_f32_e32 v6, 0x45800000, v9
	v_mul_f32_e32 v208, 0x45800000, v8
	v_cndmask_b32_e64 v204, v9, v6, s[2:3]
	v_cndmask_b32_e32 v6, v8, v208, vcc
	v_mul_f32_e32 v8, 0x45800000, v7
	v_mul_f32_e32 v9, 0x45800000, v202
	v_cndmask_b32_e64 v210, v7, v8, s[6:7]
	v_cndmask_b32_e64 v8, v202, v9, s[4:5]
	v_pk_mul_f32 v[228:229], v[204:205], v[96:97] op_sel_hi:[0,1]
	v_pk_mul_f32 v[230:231], v[204:205], v[98:99] op_sel_hi:[0,1]
	v_pk_mul_f32 v[96:97], v[6:7], v[100:101] op_sel_hi:[0,1]
	v_pk_mul_f32 v[98:99], v[6:7], v[102:103] op_sel_hi:[0,1]
	v_pk_fma_f32 v[228:229], v[228:229], v[88:89], v[2:3]
	v_pk_mul_f32 v[100:101], v[210:211], v[114:115] op_sel_hi:[0,1]
	v_pk_mul_f32 v[104:105], v[8:9], v[118:119] op_sel_hi:[0,1]
	v_pk_fma_f32 v[230:231], v[230:231], v[90:91], v[4:5]
	v_pk_fma_f32 v[98:99], v[98:99], v[90:91], v[4:5]
	v_pk_fma_f32 v[96:97], v[96:97], v[88:89], v[2:3]
	v_pk_mul_f32 v[102:103], v[210:211], v[116:117] op_sel_hi:[0,1]
	v_pk_mul_f32 v[106:107], v[8:9], v[120:121] op_sel_hi:[0,1]
	v_cvt_pk_bf16_f32 v228, v228, v229
	v_cvt_pk_bf16_f32 v229, v230, v231
	v_pk_fma_f32 v[100:101], v[88:89], v[100:101], v[2:3]
	v_pk_fma_f32 v[2:3], v[88:89], v[104:105], v[2:3]
	global_store_dwordx2 v[18:19], v[228:229], off offset:-4096
	v_cvt_pk_bf16_f32 v88, v96, v97
	v_cvt_pk_bf16_f32 v89, v98, v99
	v_pk_fma_f32 v[230:231], v[90:91], v[102:103], v[4:5]
	v_pk_fma_f32 v[4:5], v[90:91], v[106:107], v[4:5]
	global_store_dwordx2 v[20:21], v[88:89], off offset:2048
	v_cvt_pk_bf16_f32 v88, v100, v101
	v_cvt_pk_bf16_f32 v89, v230, v231
	global_store_dwordx2 v[18:19], v[88:89], off
	v_cvt_pk_bf16_f32 v2, v2, v3
	v_cvt_pk_bf16_f32 v3, v4, v5
	global_store_dwordx2 v[18:19], v[2:3], off offset:2048
	global_load_dwordx4 v[2:5], v[46:47], off offset:1024
	s_nop 0
; __device__ __forceinline__ unsigned cvt_pk(float lo, float hi) { unsigned r; asm volatile("v_cvt_pk_bf16_f32 %0, %1, %2" : "=v"(r) : "v"(lo), "v"(hi)); return r; }
; template <int PH> __device__ __forceinline__ void phase_body(const Args& args, LAS unsigned char* lds) {
;     ...
; #pragma unroll
;                         for (int j = 0; j < 4; ++j) { const f32x4 g4 = *(const f32x4*)(gain + lane * 4 + 256 * j), sc = *(const f32x4*)(mp + scoff + 256 * j) + 1.f, sh = *(const f32x4*)(mp + shoff + 256 * j); const f32x4 gs = g4 * sc;
; #pragma unroll
;                             for (int rw = 0; rw < 4; ++rw) { const f32x4 v = (f32x4){bflo(q[rw][j].x), bfhi(q[rw][j].x), bflo(q[rw][j].y), bfhi(q[rw][j].y)}; const f32x4 y = (v * ss[rw]) * gs + sh; u32x2 w;
;                                 w.x = cvt_pk(y[0], y[1]); w.y = cvt_pk(y[2], y[3]); *(u32x2*)(XC + (size_t)(R + rw) * DM + lane * 4 + 256 * j) = w; } } }
	global_load_dwordx4 v[88:91], v[14:15], off offset:1024
	global_load_dwordx4 v[228:231], v[48:49], off offset:1024
	v_mov_b32_e32 v97, v66
	v_mov_b32_e32 v66, v75
	v_mov_b32_e32 v96, v74
	v_mov_b32_e32 v74, v72
	v_mov_b32_e32 v75, v68
	v_mov_b32_e32 v68, v73
	v_mov_b32_e32 v72, v80
	v_mov_b32_e32 v73, v70
	v_mov_b32_e32 v70, v81
	v_mov_b32_e32 v80, v78
	v_mov_b32_e32 v81, v76
	v_mov_b32_e32 v76, v79
	v_pk_mul_f32 v[66:67], v[204:205], v[66:67] op_sel_hi:[0,1]
	v_pk_mul_f32 v[78:79], v[204:205], v[96:97] op_sel_hi:[0,1]
	v_pk_mul_f32 v[74:75], v[6:7], v[74:75] op_sel_hi:[0,1]
	v_pk_mul_f32 v[68:69], v[6:7], v[68:69] op_sel_hi:[0,1]
	v_pk_mul_f32 v[72:73], v[210:211], v[72:73] op_sel_hi:[0,1]
	v_pk_mul_f32 v[70:71], v[210:211], v[70:71] op_sel_hi:[0,1]
	v_pk_mul_f32 v[80:81], v[8:9], v[80:81] op_sel_hi:[0,1]
	v_pk_mul_f32 v[76:77], v[8:9], v[76:77] op_sel_hi:[0,1]
	v_pk_mul_f32 v[50:51], v[204:205], v[50:51] op_sel_hi:[0,1]
	v_pk_mul_f32 v[54:55], v[204:205], v[54:55] op_sel_hi:[0,1]
	v_pk_mul_f32 v[52:53], v[6:7], v[52:53] op_sel_hi:[0,1]
	v_pk_mul_f32 v[56:57], v[6:7], v[56:57] op_sel_hi:[0,1]
	v_pk_mul_f32 v[58:59], v[210:211], v[58:59] op_sel_hi:[0,1]
	v_pk_mul_f32 v[224:225], v[8:9], v[224:225] op_sel_hi:[0,1]
	v_pk_mul_f32 v[60:61], v[210:211], v[60:61] op_sel_hi:[0,1]
	v_pk_mul_f32 v[226:227], v[8:9], v[226:227] op_sel_hi:[0,1]
	v_mov_b32_e32 v202, v205
	v_mov_b32_e32 v208, v211
	v_pk_mul_f32 v[202:203], v[204:205], v[202:203] op_sel_hi:[0,1]
	v_pk_mul_f32 v[200:201], v[204:205], v[200:201] op_sel_hi:[0,1]
	v_pk_mul_f32 v[204:205], v[6:7], v[208:209] op_sel_hi:[0,1]
	v_pk_mul_f32 v[6:7], v[6:7], v[206:207] op_sel_hi:[0,1]
	v_pk_mul_f32 v[206:207], v[210:211], v[214:215] op_sel_hi:[0,1]
	v_pk_mul_f32 v[208:209], v[210:211], v[212:213] op_sel_hi:[0,1]
	v_pk_mul_f32 v[210:211], v[8:9], v[220:221] op_sel_hi:[0,1]
	v_pk_mul_f32 v[8:9], v[8:9], v[218:219] op_sel_hi:[0,1]
	s_waitcnt vmcnt(2)
	v_pk_add_f32 v[4:5], v[4:5], 1.0 op_sel_hi:[1,0]
	v_pk_add_f32 v[2:3], v[2:3], 1.0 op_sel_hi:[1,0]
	s_waitcnt vmcnt(1)
	v_pk_mul_f32 v[4:5], v[90:91], v[4:5]
	v_pk_mul_f32 v[2:3], v[88:89], v[2:3]
	s_waitcnt vmcnt(0)
	v_pk_fma_f32 v[66:67], v[66:67], v[4:5], v[230:231]
	v_pk_fma_f32 v[78:79], v[78:79], v[2:3], v[228:229]
	v_pk_fma_f32 v[68:69], v[68:69], v[4:5], v[230:231]
	v_pk_fma_f32 v[74:75], v[74:75], v[2:3], v[228:229]
	v_pk_fma_f32 v[70:71], v[70:71], v[4:5], v[230:231]
	v_pk_fma_f32 v[72:73], v[72:73], v[2:3], v[228:229]
	v_pk_fma_f32 v[4:5], v[76:77], v[4:5], v[230:231]
	v_pk_fma_f32 v[2:3], v[80:81], v[2:3], v[228:229]
	v_cvt_pk_bf16_f32 v76, v78, v79
	v_cvt_pk_bf16_f32 v77, v66, v67
	global_store_dwordx2 v[20:21], v[76:77], off offset:512
	v_cvt_pk_bf16_f32 v66, v74, v75
	v_cvt_pk_bf16_f32 v67, v68, v69
	global_store_dwordx2 v[20:21], v[66:67], off offset:2560
	v_cvt_pk_bf16_f32 v66, v72, v73
	v_cvt_pk_bf16_f32 v67, v70, v71
	global_store_dwordx2 v[18:19], v[66:67], off offset:512
	v_cvt_pk_bf16_f32 v2, v2, v3
	v_cvt_pk_bf16_f32 v3, v4, v5
	global_store_dwordx2 v[18:19], v[2:3], off offset:2560
	global_load_dwordx4 v[2:5], v[46:47], off offset:2048
	s_nop 0
	global_load_dwordx4 v[66:69], v[14:15], off offset:2048
	global_load_dwordx4 v[70:73], v[48:49], off offset:2048
	s_waitcnt vmcnt(2)
	v_pk_add_f32 v[2:3], v[2:3], 1.0 op_sel_hi:[1,0]
	v_pk_add_f32 v[4:5], v[4:5], 1.0 op_sel_hi:[1,0]
	s_waitcnt vmcnt(1)
	v_pk_mul_f32 v[2:3], v[66:67], v[2:3]
	v_pk_mul_f32 v[4:5], v[68:69], v[4:5]
	s_waitcnt vmcnt(0)
	v_pk_fma_f32 v[50:51], v[50:51], v[2:3], v[70:71]
	v_pk_fma_f32 v[54:55], v[54:55], v[4:5], v[72:73]
	v_cvt_pk_bf16_f32 v50, v50, v51
	v_pk_fma_f32 v[56:57], v[56:57], v[4:5], v[72:73]
	v_cvt_pk_bf16_f32 v51, v54, v55
	v_pk_fma_f32 v[52:53], v[52:53], v[2:3], v[70:71]
	v_pk_fma_f32 v[58:59], v[58:59], v[2:3], v[70:71]
	v_pk_fma_f32 v[2:3], v[224:225], v[2:3], v[70:71]
	global_store_dwordx2 v[20:21], v[50:51], off offset:1024
	v_cvt_pk_bf16_f32 v50, v52, v53
	v_cvt_pk_bf16_f32 v51, v56, v57
	v_pk_fma_f32 v[60:61], v[60:61], v[4:5], v[72:73]
	v_pk_fma_f32 v[4:5], v[226:227], v[4:5], v[72:73]
	global_store_dwordx2 v[20:21], v[50:51], off offset:3072
	v_cvt_pk_bf16_f32 v50, v58, v59
	v_cvt_pk_bf16_f32 v51, v60, v61
	global_store_dwordx2 v[18:19], v[50:51], off offset:1024
	v_cvt_pk_bf16_f32 v2, v2, v3
	v_cvt_pk_bf16_f32 v3, v4, v5
	global_store_dwordx2 v[18:19], v[2:3], off offset:3072
	global_load_dwordx4 v[2:5], v[46:47], off offset:3072
	s_nop 0
	global_load_dwordx4 v[50:53], v[14:15], off offset:3072
	global_load_dwordx4 v[54:57], v[48:49], off offset:3072
	s_waitcnt vmcnt(2)
	v_pk_add_f32 v[4:5], v[4:5], 1.0 op_sel_hi:[1,0]
	v_pk_add_f32 v[2:3], v[2:3], 1.0 op_sel_hi:[1,0]
	s_waitcnt vmcnt(1)
	v_pk_mul_f32 v[4:5], v[52:53], v[4:5]
	v_pk_mul_f32 v[2:3], v[50:51], v[2:3]
	s_waitcnt vmcnt(0)
	v_pk_fma_f32 v[200:201], v[200:201], v[4:5], v[56:57]
	v_pk_fma_f32 v[202:203], v[202:203], v[2:3], v[54:55]
	v_pk_fma_f32 v[6:7], v[6:7], v[4:5], v[56:57]
	v_pk_fma_f32 v[204:205], v[204:205], v[2:3], v[54:55]
	v_pk_fma_f32 v[208:209], v[208:209], v[4:5], v[56:57]
	v_pk_fma_f32 v[206:207], v[206:207], v[2:3], v[54:55]
	v_pk_fma_f32 v[4:5], v[8:9], v[4:5], v[56:57]
	v_pk_fma_f32 v[2:3], v[210:211], v[2:3], v[54:55]
	v_cvt_pk_bf16_f32 v8, v202, v203
	v_cvt_pk_bf16_f32 v9, v200, v201
	global_store_dwordx2 v[20:21], v[8:9], off offset:1536
	v_cvt_pk_bf16_f32 v8, v204, v205
	v_cvt_pk_bf16_f32 v9, v6, v7
	global_store_dwordx2 v[20:21], v[8:9], off offset:3584
	v_cvt_pk_bf16_f32 v6, v206, v207
	v_cvt_pk_bf16_f32 v7, v208, v209
	global_store_dwordx2 v[18:19], v[6:7], off offset:1536
	v_cvt_pk_bf16_f32 v2, v2, v3
	v_cvt_pk_bf16_f32 v3, v4, v5
	global_store_dwordx2 v[18:19], v[2:3], off offset:3584
	s_cbranch_scc1 .LBB0_981

; template <int PH> __device__ __forceinline__ void phase_body(const Args& args, LAS unsigned char* lds) {
;     ...
;                     for (int R = 4 * gw; R < MR; R += 4 * NGW) { const int b = R / NT, n = R - b * NT; const bool isc = n >= TL;
;                         if (isc && sub == 5 && l == 1) continue;
;                         const bf16_t* xr = XR + (size_t)R * DM + lane * 4; const float* mp = modl + (isc ? 32 : b) * 6144 + lane * 4;
;                         u32x2 q[4][4]; float ss[4];
; #pragma unroll
;                         for (int rw = 0; rw < 4; ++rw)
; #pragma unroll
;                             for (int j = 0; j < 4; ++j) q[rw][j] = *(const u32x2*)(xr + (size_t)rw * DM + 256 * j);
.LBB0_1214:
	s_cmp_gt_i32 s76, 9
	s_cselect_b64 s[2:3], -1, 0
	s_cmp_lt_i32 s77, 10
	s_cselect_b64 s[4:5], -1, 0
	s_or_b64 s[2:3], s[2:3], s[4:5]
	s_and_b64 vcc, exec, s[2:3]
	s_cbranch_vccnz .LBB0_1282
	v_and_b32_e32 v1, 0x3ff, v0
	v_mov_b32_e32 v2, v1
	s_add_u32 s8, s0, 0xb8
	s_waitcnt lgkmcnt(0)
	s_load_dword s21, s[0:1], 0xb8
	s_addc_u32 s9, s1, 0
	v_readfirstlane_b32 s2, v2
	s_ashr_i32 s2, s2, 4
	s_lshl_b32 s3, s26, 5
	s_and_b32 s2, s2, -4
	s_add_i32 s10, s2, s3
	s_cmp_gt_i32 s10, 0x11fff
	s_cbranch_scc1 .LBB0_1218
	v_lshlrev_b32_e32 v3, 4, v2
	v_and_b32_e32 v6, 0x3f0, v3
	v_mov_b32_e32 v7, 0
	v_mbcnt_lo_u32_b32 v3, -1, 0
	v_lshl_add_u64 v[4:5], s[30:31], 0, v[6:7]
	s_mov_b64 s[2:3], 0x45a6000
	v_mbcnt_hi_u32_b32 v3, -1, v3
	v_lshl_add_u64 v[8:9], v[4:5], 0, s[2:3]
	v_and_b32_e32 v4, 64, v3
	v_add_u32_e32 v4, 64, v4
	v_xor_b32_e32 v5, 1, v3
	v_cmp_lt_i32_e32 vcc, v5, v4
	s_mov_b64 s[2:3], 0x1000
	s_ashr_i32 s11, s10, 31
	v_cndmask_b32_e32 v5, v3, v5, vcc
	v_lshlrev_b32_e32 v78, 2, v5
	v_xor_b32_e32 v5, 2, v3
	v_cmp_lt_i32_e32 vcc, v5, v4
	s_waitcnt lgkmcnt(0)
	s_lshl_b32 s12, s21, 5
	v_and_b32_e32 v2, 63, v2
	v_cndmask_b32_e32 v5, v3, v5, vcc
	v_lshlrev_b32_e32 v79, 2, v5
	v_xor_b32_e32 v5, 4, v3
	v_cmp_lt_i32_e32 vcc, v5, v4
	s_mov_b32 s20, 0x3a800000
	s_mov_b32 s22, 0x1d92c000
	v_cndmask_b32_e32 v5, v3, v5, vcc
	v_lshlrev_b32_e32 v80, 2, v5
	v_xor_b32_e32 v5, 8, v3
	v_cmp_lt_i32_e32 vcc, v5, v4
	s_mov_b32 s23, 0x1d92d000
	s_nop 0
	v_cndmask_b32_e32 v5, v3, v5, vcc
	v_lshlrev_b32_e32 v81, 2, v5
	v_xor_b32_e32 v5, 16, v3
	v_cmp_lt_i32_e32 vcc, v5, v4
	s_nop 1
	v_cndmask_b32_e32 v5, v3, v5, vcc
	v_lshlrev_b32_e32 v82, 2, v5
	v_xor_b32_e32 v5, 32, v3
	v_cmp_lt_i32_e32 vcc, v5, v4
	s_nop 1
	v_cndmask_b32_e32 v3, v3, v5, vcc
	v_lshl_add_u64 v[4:5], s[48:49], 0, v[6:7]
	v_lshl_add_u64 v[10:11], v[4:5], 0, s[2:3]
	s_lshl_b64 s[2:3], s[10:11], 11
	s_add_u32 s14, s30, s2
	s_addc_u32 s15, s31, s3
	s_ashr_i32 s13, s12, 31
	s_lshl_b64 s[16:17], s[12:13], 11
	s_add_u32 s18, s28, s2
	s_mov_b32 s2, 0x358637bd
	v_lshlrev_b32_e32 v83, 2, v3
	v_lshlrev_b32_e32 v6, 3, v2
	s_addc_u32 s19, s29, s3
	s_movk_i32 s11, 0x1000
	v_mov_b64_e32 v[12:13], s[2:3]
	s_mov_b32 s13, 0x800000
	s_mov_b32 s98, 0x1000
	s_mov_b32 s99, 0
	v_lshl_add_u64 v[232:233], s[18:19], 0, v[6:7]
	v_lshl_add_u64 v[234:235], v[232:233], 0, s[98:99]
	global_load_dwordx2 v[18:19], v[232:233], off
	global_load_dwordx2 v[20:21], v[232:233], off offset:512
	global_load_dwordx2 v[22:23], v[232:233], off offset:1024
	global_load_dwordx2 v[24:25], v[232:233], off offset:1536
	global_load_dwordx2 v[26:27], v[232:233], off offset:2048
	global_load_dwordx2 v[28:29], v[232:233], off offset:2560
	global_load_dwordx2 v[30:31], v[232:233], off offset:3072
	global_load_dwordx2 v[32:33], v[232:233], off offset:3584
	global_load_dwordx2 v[34:35], v[234:235], off
	global_load_dwordx2 v[36:37], v[234:235], off offset:512
	global_load_dwordx2 v[38:39], v[234:235], off offset:1024
	global_load_dwordx2 v[40:41], v[234:235], off offset:1536
	global_load_dwordx2 v[58:59], v[234:235], off offset:2048
	global_load_dwordx2 v[60:61], v[234:235], off offset:2560
	global_load_dwordx2 v[92:93], v[234:235], off offset:3072
	global_load_dwordx2 v[94:95], v[234:235], off offset:3584
.LBB0_1217:
	v_lshl_add_u64 v[2:3], s[18:19], 0, v[6:7]
	s_mul_hi_i32 s2, s10, 0x38e38e39
	global_load_dwordx4 v[84:87], v[10:11], off
	v_add_co_u32_e32 v2, vcc, s11, v2
	s_lshr_b32 s3, s2, 31
	s_ashr_i32 s2, s2, 9
	v_addc_co_u32_e32 v3, vcc, 0, v3, vcc
	s_add_i32 s2, s2, s3
	s_mul_i32 s3, s2, 0xfffff700
	v_lshl_add_u64 v[4:5], s[14:15], 0, v[6:7]
	s_add_i32 s3, s10, s3
	v_add_co_u32_e32 v16, vcc, s22, v4
	s_mulk_i32 s2, 0x1800
	s_cmpk_lt_i32 s3, 0x800
	v_addc_co_u32_e32 v17, vcc, 0, v5, vcc
	s_cselect_b32 s2, s2, 0x30000
	v_add_co_u32_e32 v14, vcc, s23, v4
	s_ashr_i32 s3, s2, 31
	s_nop 0
	v_addc_co_u32_e32 v15, vcc, 0, v5, vcc
	v_lshl_add_u64 v[42:43], s[2:3], 2, v[8:9]
	v_add_co_u32_e32 v44, vcc, s11, v42
	s_add_i32 s10, s10, s12
	s_nop 0
	v_addc_co_u32_e32 v45, vcc, 0, v43, vcc
	global_load_dwordx4 v[88:91], v[44:45], off
	global_load_dwordx4 v[2:5], v[42:43], off
	s_add_u32 s14, s14, s16
	s_addc_u32 s15, s15, s17
	s_add_u32 s18, s18, s16
	s_addc_u32 s19, s19, s17
	s_cmp_lt_i32 s10, 0x12000
	s_waitcnt vmcnt(0)
	v_mov_b64_e32 v[200:201], v[18:19]
	v_mov_b64_e32 v[202:203], v[20:21]
	v_mov_b64_e32 v[204:205], v[22:23]
	v_mov_b64_e32 v[206:207], v[24:25]
	v_mov_b64_e32 v[208:209], v[26:27]
	v_mov_b64_e32 v[210:211], v[28:29]
	v_mov_b64_e32 v[212:213], v[30:31]
	v_mov_b64_e32 v[214:215], v[32:33]
	v_mov_b64_e32 v[216:217], v[34:35]
	v_mov_b64_e32 v[218:219], v[36:37]
	v_mov_b64_e32 v[220:221], v[38:39]
	v_mov_b64_e32 v[222:223], v[40:41]
	v_mov_b64_e32 v[224:225], v[58:59]
	v_mov_b64_e32 v[226:227], v[60:61]
	v_mov_b64_e32 v[228:229], v[92:93]
	v_mov_b64_e32 v[230:231], v[94:95]
	s_cbranch_scc0 .Lnpf_n1
	v_lshl_add_u64 v[232:233], s[18:19], 0, v[6:7]
	v_lshl_add_u64 v[234:235], v[232:233], 0, s[98:99]
	global_load_dwordx2 v[18:19], v[232:233], off
	global_load_dwordx2 v[20:21], v[232:233], off offset:512
	global_load_dwordx2 v[22:23], v[232:233], off offset:1024
	global_load_dwordx2 v[24:25], v[232:233], off offset:1536
	global_load_dwordx2 v[26:27], v[232:233], off offset:2048
	global_load_dwordx2 v[28:29], v[232:233], off offset:2560
	global_load_dwordx2 v[30:31], v[232:233], off offset:3072
	global_load_dwordx2 v[32:33], v[232:233], off offset:3584
	global_load_dwordx2 v[34:35], v[234:235], off
	global_load_dwordx2 v[36:37], v[234:235], off offset:512
	global_load_dwordx2 v[38:39], v[234:235], off offset:1024
	global_load_dwordx2 v[40:41], v[234:235], off offset:1536
	global_load_dwordx2 v[58:59], v[234:235], off offset:2048
	global_load_dwordx2 v[60:61], v[234:235], off offset:2560
	global_load_dwordx2 v[92:93], v[234:235], off offset:3072
	global_load_dwordx2 v[94:95], v[234:235], off offset:3584
; template <int PH> __device__ __forceinline__ void phase_body(const Args& args, LAS unsigned char* lds) {
;     ...
;                         for (int rw = 0; rw < 4; ++rw) { float s_ = 0.f;
; #pragma unroll
;                             for (int j = 0; j < 4; ++j) { const float a0 = bflo(q[rw][j].x), a1 = bfhi(q[rw][j].x), a2 = bflo(q[rw][j].y), a3 = bfhi(q[rw][j].y); s_ += (a0 * a0 + a1 * a1) + (a2 * a2 + a3 * a3); }
.Lnpf_n1:
	v_and_b32_e32 v97, 0xffff0000, v200
	v_and_b32_e32 v99, 0xffff0000, v201
	v_and_b32_e32 v63, 0xffff0000, v203
	v_and_b32_e32 v62, 0xffff0000, v202
	v_and_b32_e32 v47, 0xffff0000, v204
	v_lshlrev_b32_e32 v50, 16, v205
	v_and_b32_e32 v51, 0xffff0000, v205
	v_lshlrev_b32_e32 v205, 16, v206
	v_and_b32_e32 v101, 0xffff0000, v208
	v_and_b32_e32 v103, 0xffff0000, v209
	v_lshlrev_b32_e32 v96, 16, v200
	v_lshlrev_b32_e32 v98, 16, v201
	v_lshlrev_b32_e32 v71, 16, v203
	v_lshlrev_b32_e32 v70, 16, v202
	v_lshlrev_b32_e32 v46, 16, v204
	v_and_b32_e32 v203, 0xffff0000, v206
	v_lshlrev_b32_e32 v200, 16, v207
	v_and_b32_e32 v201, 0xffff0000, v207
	v_lshlrev_b32_e32 v100, 16, v208
	v_lshlrev_b32_e32 v102, 16, v209
	v_lshlrev_b32_e32 v69, 16, v211
	v_and_b32_e32 v65, 0xffff0000, v211
	v_and_b32_e32 v64, 0xffff0000, v210
	v_and_b32_e32 v49, 0xffff0000, v212
	v_and_b32_e32 v53, 0xffff0000, v213
	v_lshlrev_b32_e32 v211, 16, v214
	v_and_b32_e32 v209, 0xffff0000, v214
	v_lshlrev_b32_e32 v206, 16, v215
	v_and_b32_e32 v207, 0xffff0000, v215
	v_mul_f32_e32 v202, v99, v99
	v_pk_mul_f32 v[104:105], v[62:63], v[62:63]
	v_mul_f32_e32 v204, v97, v97
	v_mov_b32_e32 v107, v205
	v_mul_f32_e32 v208, v47, v47
	v_mul_f32_e32 v214, v103, v103
	v_mul_f32_e32 v106, v101, v101
	v_and_b32_e32 v115, 0xffff0000, v216
	v_and_b32_e32 v117, 0xffff0000, v217
	v_and_b32_e32 v67, 0xffff0000, v219
	v_and_b32_e32 v66, 0xffff0000, v218
	v_and_b32_e32 v215, 0xffff0000, v222
	v_and_b32_e32 v119, 0xffff0000, v224
	v_and_b32_e32 v121, 0xffff0000, v225
	v_lshlrev_b32_e32 v68, 16, v210
	v_lshlrev_b32_e32 v48, 16, v212
	v_lshlrev_b32_e32 v52, 16, v213
	v_mul_f32_e32 v210, v51, v51
	v_pk_mul_f32 v[108:109], v[64:65], v[64:65]
	v_mov_b32_e32 v111, v211
	v_mul_f32_e32 v110, v49, v49
	v_mul_f32_e32 v112, v53, v53
	v_lshlrev_b32_e32 v114, 16, v216
	v_lshlrev_b32_e32 v116, 16, v217
	v_lshlrev_b32_e32 v77, 16, v219
	v_lshlrev_b32_e32 v76, 16, v218
	v_lshlrev_b32_e32 v54, 16, v220
	v_and_b32_e32 v55, 0xffff0000, v220
	v_lshlrev_b32_e32 v56, 16, v221
	v_and_b32_e32 v57, 0xffff0000, v221
	v_lshlrev_b32_e32 v217, 16, v222
	v_lshlrev_b32_e32 v212, 16, v223
	v_and_b32_e32 v213, 0xffff0000, v223
	v_lshlrev_b32_e32 v118, 16, v224
	v_lshlrev_b32_e32 v120, 16, v225
	v_lshlrev_b32_e32 v75, 16, v227
	v_lshlrev_b32_e32 v74, 16, v226
	v_and_b32_e32 v73, 0xffff0000, v227
	v_and_b32_e32 v72, 0xffff0000, v226
	v_lshlrev_b32_e32 v224, 16, v228
	v_and_b32_e32 v225, 0xffff0000, v228
	v_lshlrev_b32_e32 v226, 16, v229
	v_and_b32_e32 v227, 0xffff0000, v229
	v_lshlrev_b32_e32 v223, 16, v230
	v_and_b32_e32 v221, 0xffff0000, v230
	v_lshlrev_b32_e32 v218, 16, v231
	v_and_b32_e32 v219, 0xffff0000, v231
	v_pk_fma_f32 v[228:229], v[98:99], v[98:99], v[202:203] op_sel_hi:[1,1,0]
	v_pk_fma_f32 v[230:231], v[70:71], v[70:71], v[104:105]
	v_pk_fma_f32 v[104:105], v[96:97], v[96:97], v[204:205] op_sel_hi:[1,1,0]
	v_pk_fma_f32 v[122:123], v[46:47], v[46:47], v[208:209] op_sel_hi:[1,1,0]
	v_pk_fma_f32 v[126:127], v[102:103], v[102:103], v[214:215] op_sel_hi:[1,1,0]
	v_pk_fma_f32 v[128:129], v[100:101], v[100:101], v[106:107] op_sel_hi:[1,1,0]
	v_mul_f32_e32 v202, v117, v117
	v_pk_mul_f32 v[132:133], v[66:67], v[66:67]
	v_mul_f32_e32 v208, v115, v115
	v_mul_f32_e32 v220, v121, v121
	v_mul_f32_e32 v222, v119, v119
	v_mul_f32_e32 v140, v200, v200
	v_mul_f32_e32 v141, v201, v201
	v_mul_f32_e32 v142, v206, v206
	v_mul_f32_e32 v143, v207, v207
	v_pk_fma_f32 v[124:125], v[50:51], v[50:51], v[210:211] op_sel_hi:[1,1,0]
	v_pk_fma_f32 v[108:109], v[68:69], v[68:69], v[108:109]
	v_pk_fma_f32 v[130:131], v[48:49], v[48:49], v[110:111] op_sel_hi:[1,1,0]
	v_pk_fma_f32 v[112:113], v[52:53], v[52:53], v[112:113] op_sel_hi:[1,1,0]
	v_mov_b32_e32 v135, v217
	v_mul_f32_e32 v216, v57, v57
	v_pk_mul_f32 v[136:137], v[72:73], v[72:73]
	v_mov_b32_e32 v139, v223
	v_mul_f32_e32 v134, v225, v225
	v_mul_f32_e32 v138, v227, v227
	v_mov_b32_e32 v204, v104
	v_mov_b32_e32 v106, v228
	v_pk_add_f32 v[228:229], v[104:105], v[228:229]
	v_mov_b32_e32 v210, v128
	v_mov_b32_e32 v110, v126
	v_pk_add_f32 v[104:105], v[128:129], v[126:127]
	v_pk_fma_f32 v[126:127], v[116:117], v[116:117], v[202:203] op_sel_hi:[1,1,0]
	v_pk_fma_f32 v[128:129], v[76:77], v[76:77], v[132:133]
	v_pk_fma_f32 v[132:133], v[114:115], v[114:115], v[208:209] op_sel_hi:[1,1,0]
	v_pk_fma_f32 v[144:145], v[120:121], v[120:121], v[220:221] op_sel_hi:[1,1,0]
	v_pk_fma_f32 v[146:147], v[118:119], v[118:119], v[222:223] op_sel_hi:[1,1,0]
	v_mul_f32_e32 v152, v203, v203
	v_mul_f32_e32 v153, v209, v209
	v_mul_f32_e32 v214, v55, v55
	v_pk_add_f32 v[230:231], v[230:231], v[230:231] op_sel:[0,1] op_sel_hi:[1,0]
	v_mov_b32_e32 v123, v140
	v_mov_b32_e32 v125, v141
	v_pk_add_f32 v[108:109], v[108:109], v[108:109] op_sel:[0,1] op_sel_hi:[1,0]
	v_mov_b32_e32 v131, v142
	v_mov_b32_e32 v113, v143
	v_pk_fma_f32 v[142:143], v[56:57], v[56:57], v[216:217] op_sel_hi:[1,1,0]
	v_pk_fma_f32 v[136:137], v[74:75], v[74:75], v[136:137]
	v_pk_fma_f32 v[148:149], v[224:225], v[224:225], v[134:135] op_sel_hi:[1,1,0]
	v_pk_fma_f32 v[150:151], v[226:227], v[226:227], v[138:139] op_sel_hi:[1,1,0]
	v_pk_mul_f32 v[106:107], v[204:205], v[106:107]
	v_pk_mul_f32 v[110:111], v[210:211], v[110:111]
	v_mov_b32_e32 v216, v132
	v_mov_b32_e32 v134, v126
	v_mov_b32_e32 v222, v146
	v_mov_b32_e32 v138, v144
	v_mul_f32_e32 v154, v215, v215
	v_mul_f32_e32 v155, v212, v212
	v_mul_f32_e32 v156, v213, v213
	v_mul_f32_e32 v157, v221, v221
	v_mul_f32_e32 v158, v218, v218
	v_mul_f32_e32 v159, v219, v219
	v_pk_fma_f32 v[140:141], v[54:55], v[54:55], v[214:215] op_sel_hi:[1,1,0]
	v_mov_b32_e32 v231, v152
	v_pk_add_f32 v[122:123], v[122:123], v[124:125]
; __device__ __forceinline__ unsigned cvt_pk(float lo, float hi) { unsigned r; asm volatile("v_cvt_pk_bf16_f32 %0, %1, %2" : "=v"(r) : "v"(lo), "v"(hi)); return r; }
; __device__ __forceinline__ float wave_sum(float v) {
; #pragma unroll
;     for (int o = 1; o < 64; o <<= 1) v += __shfl_xor(v, o);
;     return v;
; template <int PH> __device__ __forceinline__ void phase_body(const Args& args, LAS unsigned char* lds) {
;     ...
;                         for (int rw = 0; rw < 4; ++rw) { float s_ = 0.f;
; #pragma unroll
;                             for (int j = 0; j < 4; ++j) { const float a0 = bflo(q[rw][j].x), a1 = bfhi(q[rw][j].x), a2 = bflo(q[rw][j].y), a3 = bfhi(q[rw][j].y); s_ += (a0 * a0 + a1 * a1) + (a2 * a2 + a3 * a3); }
;                             ss[rw] = rsqrtf(wave_sum(s_) * (1.f / DM) + EPS); }
; #pragma unroll
;                         for (int j = 0; j < 4; ++j) { const f32x4 g4 = *(const f32x4*)(gain + lane * 4 + 256 * j), sc = *(const f32x4*)(mp + scoff + 256 * j) + 1.f, sh = *(const f32x4*)(mp + shoff + 256 * j); const f32x4 gs = g4 * sc;
; #pragma unroll
;                             for (int rw = 0; rw < 4; ++rw) { const f32x4 v = (f32x4){bflo(q[rw][j].x), bfhi(q[rw][j].x), bflo(q[rw][j].y), bfhi(q[rw][j].y)}; const f32x4 y = (v * ss[rw]) * gs + sh; u32x2 w;
;                                 w.x = cvt_pk(y[0], y[1]); w.y = cvt_pk(y[2], y[3]); *(u32x2*)(XC + (size_t)(R + rw) * DM + lane * 4 + 256 * j) = w; } } }
	v_mov_b32_e32 v109, v153
	v_pk_add_f32 v[112:113], v[130:131], v[112:113]
	v_pk_add_f32 v[124:125], v[132:133], v[126:127]
	v_pk_add_f32 v[126:127], v[128:129], v[128:129] op_sel:[0,1] op_sel_hi:[1,0]
	v_pk_add_f32 v[128:129], v[146:147], v[144:145]
	v_pk_add_f32 v[130:131], v[136:137], v[136:137] op_sel:[0,1] op_sel_hi:[1,0]
	v_mov_b32_e32 v229, v107
	v_mov_b32_e32 v105, v111
	v_pk_mul_f32 v[106:107], v[216:217], v[134:135]
	v_pk_mul_f32 v[132:133], v[222:223], v[138:139]
	v_mov_b32_e32 v141, v155
	v_mov_b32_e32 v143, v156
	v_mov_b32_e32 v149, v158
	v_mov_b32_e32 v151, v159
	v_mov_b32_e32 v127, v154
	v_mov_b32_e32 v131, v157
	v_pk_add_f32 v[228:229], v[228:229], v[230:231]
	v_pk_add_f32 v[230:231], v[104:105], v[108:109]
	v_mov_b32_e32 v125, v107
	v_mov_b32_e32 v129, v133
	v_pk_add_f32 v[110:111], v[140:141], v[142:143]
	v_pk_add_f32 v[134:135], v[148:149], v[150:151]
	v_pk_add_f32 v[228:229], v[228:229], v[122:123]
	v_pk_add_f32 v[230:231], v[230:231], v[112:113]
	v_pk_add_f32 v[104:105], v[124:125], v[126:127]
	v_pk_add_f32 v[106:107], v[128:129], v[130:131]
	v_mov_b32_e32 v108, v230
	v_mov_b32_e32 v109, v228
	v_mov_b32_e32 v228, v231
	v_pk_add_f32 v[230:231], v[104:105], v[110:111]
	v_pk_add_f32 v[104:105], v[106:107], v[134:135]
	v_pk_add_f32 v[228:229], v[108:109], v[228:229]
	v_mov_b32_e32 v106, v104
	v_mov_b32_e32 v107, v230
	v_mov_b32_e32 v230, v105
	v_pk_add_f32 v[88:89], v[88:89], 1.0 op_sel_hi:[1,0]
	ds_bpermute_b32 v105, v78, v229
	ds_bpermute_b32 v104, v78, v228
	v_pk_add_f32 v[230:231], v[106:107], v[230:231]
	v_pk_mul_f32 v[84:85], v[84:85], v[88:89]
	ds_bpermute_b32 v89, v78, v231
	ds_bpermute_b32 v88, v78, v230
	v_pk_add_f32 v[90:91], v[90:91], 1.0 op_sel_hi:[1,0]
	s_waitcnt lgkmcnt(0)
	v_pk_add_f32 v[88:89], v[230:231], v[88:89]
	v_pk_mul_f32 v[86:87], v[86:87], v[90:91]
	v_pk_add_f32 v[90:91], v[228:229], v[104:105]
	ds_bpermute_b32 v229, v79, v91
	ds_bpermute_b32 v228, v79, v90
	ds_bpermute_b32 v231, v79, v89
	ds_bpermute_b32 v230, v79, v88
	s_waitcnt lgkmcnt(2)
	v_pk_add_f32 v[90:91], v[90:91], v[228:229]
	ds_bpermute_b32 v229, v80, v91
	ds_bpermute_b32 v228, v80, v90
	s_waitcnt lgkmcnt(2)
	v_pk_add_f32 v[88:89], v[88:89], v[230:231]
	ds_bpermute_b32 v231, v80, v89
	ds_bpermute_b32 v230, v80, v88
	s_waitcnt lgkmcnt(2)
	v_pk_add_f32 v[90:91], v[90:91], v[228:229]
	ds_bpermute_b32 v229, v81, v91
	ds_bpermute_b32 v228, v81, v90
	s_waitcnt lgkmcnt(2)
	v_pk_add_f32 v[88:89], v[88:89], v[230:231]
	ds_bpermute_b32 v231, v81, v89
	ds_bpermute_b32 v230, v81, v88
	s_waitcnt lgkmcnt(2)
	v_pk_add_f32 v[90:91], v[90:91], v[228:229]
	ds_bpermute_b32 v229, v82, v91
	ds_bpermute_b32 v228, v82, v90
	s_waitcnt lgkmcnt(2)
	v_pk_add_f32 v[88:89], v[88:89], v[230:231]
	ds_bpermute_b32 v231, v82, v89
	ds_bpermute_b32 v230, v82, v88
	s_waitcnt lgkmcnt(2)
	v_pk_add_f32 v[90:91], v[90:91], v[228:229]
	ds_bpermute_b32 v229, v83, v91
	ds_bpermute_b32 v228, v83, v90
	s_waitcnt lgkmcnt(2)
	v_pk_add_f32 v[88:89], v[88:89], v[230:231]
	ds_bpermute_b32 v231, v83, v89
	ds_bpermute_b32 v230, v83, v88
	s_waitcnt lgkmcnt(2)
	v_pk_add_f32 v[90:91], v[90:91], v[228:229]
	s_nop 0
	v_pk_fma_f32 v[90:91], v[90:91], s[20:21], v[12:13] op_sel_hi:[1,0,0]
	s_waitcnt lgkmcnt(0)
	v_pk_add_f32 v[88:89], v[88:89], v[230:231]
	v_mul_f32_e32 v202, 0x4b800000, v91
	v_pk_fma_f32 v[88:89], v[88:89], s[20:21], v[12:13] op_sel_hi:[1,0,0]
	v_cmp_gt_f32_e64 s[2:3], s13, v91
	v_mul_f32_e32 v204, 0x4b800000, v90
	v_cmp_gt_f32_e32 vcc, s13, v90
	v_cndmask_b32_e64 v202, v91, v202, s[2:3]
	v_mul_f32_e32 v208, 0x4b800000, v89
	v_mul_f32_e32 v210, 0x4b800000, v88
	v_cmp_gt_f32_e64 s[4:5], s13, v88
	v_cmp_gt_f32_e64 s[6:7], s13, v89
	v_cndmask_b32_e32 v204, v90, v204, vcc
	v_rsq_f32_e32 v202, v202
	v_cndmask_b32_e64 v208, v89, v208, s[6:7]
	v_cndmask_b32_e64 v210, v88, v210, s[4:5]
	v_rsq_f32_e32 v204, v204
	v_rsq_f32_e32 v208, v208
	v_rsq_f32_e32 v210, v210
	v_mul_f32_e32 v214, 0x45800000, v202
	v_mul_f32_e32 v220, 0x45800000, v204
	v_cndmask_b32_e64 v216, v202, v214, s[2:3]
	v_mul_f32_e32 v202, 0x45800000, v208
	v_mul_f32_e32 v214, 0x45800000, v210
	v_cndmask_b32_e32 v204, v204, v220, vcc
	v_cndmask_b32_e64 v222, v208, v202, s[6:7]
	v_cndmask_b32_e64 v210, v210, v214, s[4:5]
	v_pk_mul_f32 v[88:89], v[216:217], v[96:97] op_sel_hi:[0,1]
	v_pk_mul_f32 v[90:91], v[216:217], v[98:99] op_sel_hi:[0,1]
	v_pk_mul_f32 v[228:229], v[204:205], v[100:101] op_sel_hi:[0,1]
	v_pk_mul_f32 v[230:231], v[204:205], v[102:103] op_sel_hi:[0,1]
	v_pk_fma_f32 v[88:89], v[88:89], v[84:85], v[2:3]
	v_pk_mul_f32 v[96:97], v[222:223], v[114:115] op_sel_hi:[0,1]
	v_pk_mul_f32 v[100:101], v[210:211], v[118:119] op_sel_hi:[0,1]
	v_pk_fma_f32 v[90:91], v[90:91], v[86:87], v[4:5]
	v_pk_fma_f32 v[230:231], v[230:231], v[86:87], v[4:5]
	v_pk_fma_f32 v[228:229], v[228:229], v[84:85], v[2:3]
	v_pk_mul_f32 v[98:99], v[222:223], v[116:117] op_sel_hi:[0,1]
	v_pk_mul_f32 v[102:103], v[210:211], v[120:121] op_sel_hi:[0,1]
	v_cvt_pk_bf16_f32 v88, v88, v89
	v_cvt_pk_bf16_f32 v89, v90, v91
	v_pk_fma_f32 v[96:97], v[84:85], v[96:97], v[2:3]
	v_pk_fma_f32 v[2:3], v[84:85], v[100:101], v[2:3]
	global_store_dwordx2 v[14:15], v[88:89], off offset:-4096
	v_cvt_pk_bf16_f32 v84, v228, v229
	v_cvt_pk_bf16_f32 v85, v230, v231
	v_pk_fma_f32 v[90:91], v[86:87], v[98:99], v[4:5]
	v_pk_fma_f32 v[4:5], v[86:87], v[102:103], v[4:5]
	global_store_dwordx2 v[16:17], v[84:85], off offset:2048
	v_cvt_pk_bf16_f32 v84, v96, v97
	v_cvt_pk_bf16_f32 v85, v90, v91
	global_store_dwordx2 v[14:15], v[84:85], off
	v_cvt_pk_bf16_f32 v2, v2, v3
	v_cvt_pk_bf16_f32 v3, v4, v5
	global_store_dwordx2 v[14:15], v[2:3], off offset:2048
; __device__ __forceinline__ unsigned cvt_pk(float lo, float hi) { unsigned r; asm volatile("v_cvt_pk_bf16_f32 %0, %1, %2" : "=v"(r) : "v"(lo), "v"(hi)); return r; }
; template <int PH> __device__ __forceinline__ void phase_body(const Args& args, LAS unsigned char* lds) {
;     ...
; #pragma unroll
;                         for (int j = 0; j < 4; ++j) { const f32x4 g4 = *(const f32x4*)(gain + lane * 4 + 256 * j), sc = *(const f32x4*)(mp + scoff + 256 * j) + 1.f, sh = *(const f32x4*)(mp + shoff + 256 * j); const f32x4 gs = g4 * sc;
; #pragma unroll
;                             for (int rw = 0; rw < 4; ++rw) { const f32x4 v = (f32x4){bflo(q[rw][j].x), bfhi(q[rw][j].x), bflo(q[rw][j].y), bfhi(q[rw][j].y)}; const f32x4 y = (v * ss[rw]) * gs + sh; u32x2 w;
;                                 w.x = cvt_pk(y[0], y[1]); w.y = cvt_pk(y[2], y[3]); *(u32x2*)(XC + (size_t)(R + rw) * DM + lane * 4 + 256 * j) = w; } } }
	global_load_dwordx4 v[2:5], v[44:45], off offset:1024
	s_nop 0
	global_load_dwordx4 v[84:87], v[10:11], off offset:1024
	global_load_dwordx4 v[88:91], v[42:43], off offset:1024
	v_mov_b32_e32 v229, v62
	v_mov_b32_e32 v62, v71
	v_mov_b32_e32 v228, v70
	v_mov_b32_e32 v70, v68
	v_mov_b32_e32 v71, v64
	v_mov_b32_e32 v64, v69
	v_mov_b32_e32 v68, v76
	v_mov_b32_e32 v69, v66
	v_mov_b32_e32 v66, v77
	v_mov_b32_e32 v76, v74
	v_mov_b32_e32 v77, v72
	v_mov_b32_e32 v72, v75
	v_pk_mul_f32 v[62:63], v[216:217], v[62:63] op_sel_hi:[0,1]
	v_pk_mul_f32 v[74:75], v[216:217], v[228:229] op_sel_hi:[0,1]
	v_pk_mul_f32 v[70:71], v[204:205], v[70:71] op_sel_hi:[0,1]
	v_pk_mul_f32 v[64:65], v[204:205], v[64:65] op_sel_hi:[0,1]
	v_pk_mul_f32 v[68:69], v[222:223], v[68:69] op_sel_hi:[0,1]
	v_pk_mul_f32 v[66:67], v[222:223], v[66:67] op_sel_hi:[0,1]
	v_pk_mul_f32 v[76:77], v[210:211], v[76:77] op_sel_hi:[0,1]
	v_pk_mul_f32 v[72:73], v[210:211], v[72:73] op_sel_hi:[0,1]
	v_pk_mul_f32 v[46:47], v[216:217], v[46:47] op_sel_hi:[0,1]
	v_pk_mul_f32 v[50:51], v[216:217], v[50:51] op_sel_hi:[0,1]
	v_pk_mul_f32 v[48:49], v[204:205], v[48:49] op_sel_hi:[0,1]
	v_pk_mul_f32 v[52:53], v[204:205], v[52:53] op_sel_hi:[0,1]
	v_pk_mul_f32 v[54:55], v[222:223], v[54:55] op_sel_hi:[0,1]
	v_pk_mul_f32 v[224:225], v[210:211], v[224:225] op_sel_hi:[0,1]
	v_pk_mul_f32 v[56:57], v[222:223], v[56:57] op_sel_hi:[0,1]
	v_pk_mul_f32 v[226:227], v[210:211], v[226:227] op_sel_hi:[0,1]
	v_mov_b32_e32 v202, v205
	v_mov_b32_e32 v208, v211
	v_mov_b32_e32 v214, v217
	v_mov_b32_e32 v220, v223
	v_pk_mul_f32 v[202:203], v[216:217], v[202:203] op_sel_hi:[0,1]
	v_pk_mul_f32 v[200:201], v[216:217], v[200:201] op_sel_hi:[0,1]
	v_pk_mul_f32 v[208:209], v[204:205], v[208:209] op_sel_hi:[0,1]
	v_pk_mul_f32 v[204:205], v[204:205], v[206:207] op_sel_hi:[0,1]
	v_pk_mul_f32 v[206:207], v[222:223], v[214:215] op_sel_hi:[0,1]
	v_pk_mul_f32 v[214:215], v[210:211], v[220:221] op_sel_hi:[0,1]
	v_pk_mul_f32 v[212:213], v[222:223], v[212:213] op_sel_hi:[0,1]
	v_pk_mul_f32 v[210:211], v[210:211], v[218:219] op_sel_hi:[0,1]
	s_waitcnt vmcnt(2)
	v_pk_add_f32 v[4:5], v[4:5], 1.0 op_sel_hi:[1,0]
	v_pk_add_f32 v[2:3], v[2:3], 1.0 op_sel_hi:[1,0]
	s_waitcnt vmcnt(1)
	v_pk_mul_f32 v[4:5], v[86:87], v[4:5]
	v_pk_mul_f32 v[2:3], v[84:85], v[2:3]
	s_waitcnt vmcnt(0)
	v_pk_fma_f32 v[62:63], v[62:63], v[4:5], v[90:91]
	v_pk_fma_f32 v[74:75], v[74:75], v[2:3], v[88:89]
	v_pk_fma_f32 v[64:65], v[64:65], v[4:5], v[90:91]
	v_pk_fma_f32 v[70:71], v[70:71], v[2:3], v[88:89]
	v_pk_fma_f32 v[66:67], v[66:67], v[4:5], v[90:91]
	v_pk_fma_f32 v[68:69], v[68:69], v[2:3], v[88:89]
	v_pk_fma_f32 v[4:5], v[72:73], v[4:5], v[90:91]
	v_pk_fma_f32 v[2:3], v[76:77], v[2:3], v[88:89]
	v_cvt_pk_bf16_f32 v72, v74, v75
	v_cvt_pk_bf16_f32 v73, v62, v63
	global_store_dwordx2 v[16:17], v[72:73], off offset:512
	v_cvt_pk_bf16_f32 v62, v70, v71
	v_cvt_pk_bf16_f32 v63, v64, v65
	global_store_dwordx2 v[16:17], v[62:63], off offset:2560
	v_cvt_pk_bf16_f32 v62, v68, v69
	v_cvt_pk_bf16_f32 v63, v66, v67
	global_store_dwordx2 v[14:15], v[62:63], off offset:512
	v_cvt_pk_bf16_f32 v2, v2, v3
	v_cvt_pk_bf16_f32 v3, v4, v5
	global_store_dwordx2 v[14:15], v[2:3], off offset:2560
	global_load_dwordx4 v[2:5], v[44:45], off offset:2048
	s_nop 0
	global_load_dwordx4 v[62:65], v[10:11], off offset:2048
	global_load_dwordx4 v[66:69], v[42:43], off offset:2048
	s_waitcnt vmcnt(2)
	v_pk_add_f32 v[2:3], v[2:3], 1.0 op_sel_hi:[1,0]
	v_pk_add_f32 v[4:5], v[4:5], 1.0 op_sel_hi:[1,0]
	s_waitcnt vmcnt(1)
	v_pk_mul_f32 v[2:3], v[62:63], v[2:3]
	v_pk_mul_f32 v[4:5], v[64:65], v[4:5]
	s_waitcnt vmcnt(0)
	v_pk_fma_f32 v[46:47], v[46:47], v[2:3], v[66:67]
	v_pk_fma_f32 v[50:51], v[50:51], v[4:5], v[68:69]
	v_cvt_pk_bf16_f32 v46, v46, v47
	v_pk_fma_f32 v[52:53], v[52:53], v[4:5], v[68:69]
	v_cvt_pk_bf16_f32 v47, v50, v51
	v_pk_fma_f32 v[48:49], v[48:49], v[2:3], v[66:67]
	v_pk_fma_f32 v[54:55], v[54:55], v[2:3], v[66:67]
	v_pk_fma_f32 v[2:3], v[224:225], v[2:3], v[66:67]
	global_store_dwordx2 v[16:17], v[46:47], off offset:1024
	v_cvt_pk_bf16_f32 v46, v48, v49
	v_cvt_pk_bf16_f32 v47, v52, v53
	v_pk_fma_f32 v[56:57], v[56:57], v[4:5], v[68:69]
	v_pk_fma_f32 v[4:5], v[226:227], v[4:5], v[68:69]
	global_store_dwordx2 v[16:17], v[46:47], off offset:3072
	v_cvt_pk_bf16_f32 v46, v54, v55
	v_cvt_pk_bf16_f32 v47, v56, v57
	global_store_dwordx2 v[14:15], v[46:47], off offset:1024
	v_cvt_pk_bf16_f32 v2, v2, v3
	v_cvt_pk_bf16_f32 v3, v4, v5
	global_store_dwordx2 v[14:15], v[2:3], off offset:3072
	global_load_dwordx4 v[2:5], v[44:45], off offset:3072
	s_nop 0
	global_load_dwordx4 v[46:49], v[10:11], off offset:3072
	global_load_dwordx4 v[50:53], v[42:43], off offset:3072
	s_waitcnt vmcnt(2)
	v_pk_add_f32 v[4:5], v[4:5], 1.0 op_sel_hi:[1,0]
	v_pk_add_f32 v[2:3], v[2:3], 1.0 op_sel_hi:[1,0]
	s_waitcnt vmcnt(1)
	v_pk_mul_f32 v[4:5], v[48:49], v[4:5]
	v_pk_mul_f32 v[2:3], v[46:47], v[2:3]
	s_waitcnt vmcnt(0)
	v_pk_fma_f32 v[200:201], v[200:201], v[4:5], v[52:53]
	v_pk_fma_f32 v[202:203], v[202:203], v[2:3], v[50:51]
	v_pk_fma_f32 v[208:209], v[208:209], v[2:3], v[50:51]
	v_pk_fma_f32 v[206:207], v[206:207], v[2:3], v[50:51]
	v_pk_fma_f32 v[2:3], v[214:215], v[2:3], v[50:51]
	v_pk_fma_f32 v[204:205], v[204:205], v[4:5], v[52:53]
	v_pk_fma_f32 v[212:213], v[212:213], v[4:5], v[52:53]
	v_pk_fma_f32 v[4:5], v[210:211], v[4:5], v[52:53]
	v_cvt_pk_bf16_f32 v202, v202, v203
	v_cvt_pk_bf16_f32 v203, v200, v201
	global_store_dwordx2 v[16:17], v[202:203], off offset:1536
	v_cvt_pk_bf16_f32 v200, v208, v209
	v_cvt_pk_bf16_f32 v201, v204, v205
	global_store_dwordx2 v[16:17], v[200:201], off offset:3584
	v_cvt_pk_bf16_f32 v16, v206, v207
	v_cvt_pk_bf16_f32 v17, v212, v213
	global_store_dwordx2 v[14:15], v[16:17], off offset:1536
	v_cvt_pk_bf16_f32 v2, v2, v3
	v_cvt_pk_bf16_f32 v3, v4, v5
	global_store_dwordx2 v[14:15], v[2:3], off offset:3584
	s_cbranch_scc1 .LBB0_1217
